# phase 1 (NT=22) unit order: each XCD takes 32 consecutive units per round (better L2 reuse of A/B tiles)
# speedup vs baseline: 1.0054x; 1.0054x over previous
; template <int EPI>
; __device__ __forceinline__ void gemm_phase(const Params& p, const u16* __restrict__ A, int lda, const u16* __restrict__ BT, int ldb,
;                            int K, int N, u16* __restrict__ outb, int ldo, int resid_in, int boff) {
;     ...
;   const int NT = N / 128;
;   const int tiles = (MT / 256) * NT;
;   const int KTALL = K / 64;
;   float* part = (float*)(p.ws + O_PART);
;   int bstart = (int)blockIdx.x - boff;
;   if (bstart < 0) bstart += gridDim.x;
;   const size_t a64 = (size_t)64 * lda, b64 = (size_t)64 * ldb;
;   const int G = gridDim.x;
;   int t_full = tiles, split = 1;
;   if (EPI == EPI_RES) {
;     const int tail = tiles % G;
;     if (tail > 0 && (G % tail) == 0 && (KTALL % (G / tail)) == 0) { t_full = tiles - tail; const int smax = (KTALL >= 64) ? 8 : 4; split = (G / tail) > smax ? smax : (G / tail); }
;   }
;   const int units = t_full + (tiles - t_full) * split;
.Lgm_par1:
	s_add_u32 s16, s96, 0x2f08100
	s_addc_u32 s17, s97, 0
	s_add_u32 s20, s96, 0x0
	s_addc_u32 s21, s97, 0
	s_add_u32 s22, s96, 0x7108100
	s_addc_u32 s23, s97, 0
	s_movk_i32 s24, 0x1600
	s_mov_b32 s25, 22
	s_mov_b32 s26, 0xba2e8bb
	s_mov_b32 s27, 4
	s_movk_i32 s28, 0x5ac
	s_movk_i32 s29, 0x500
	s_mov_b32 s30, 0
	s_movk_i32 s38, 0x5ac
	s_mov_b32 s39, 16
	s_mov_b32 s44, 0
	s_mov_b32 s45, 11
	s_mov_b32 s46, 11
	s_branch .Lgm_common

; template <int EPI>
; __device__ __forceinline__ void gemm_phase(const Params& p, const u16* __restrict__ A, int lda, const u16* __restrict__ BT, int ldb,
;                            int K, int N, u16* __restrict__ outb, int ldo, int resid_in, int boff) {
;     ...
;   for (int un = bstart; un < units; un += G) {
;     int tl = un, kbeg = 0, KT = KTALL;
;     bool part_unit = false;
;     if (un >= t_full) { const int v = un - t_full; tl = t_full + v / split; KT = KTALL / split; kbeg = (v % split) * KT; part_unit = true; }
;     int mt = tl / NT, nt = tl % NT;
;     if (EPI == EPI_RES && NT == 8 && G == 256 && !part_unit) {
;       const int rr = tl >> 8, bb = tl & 255;
;       const int xx = bb & 7, jj = bb >> 3;
;       mt = rr * 32 + xx * 4 + (jj >> 3);
;       nt = jj & 7;
;     } else if ((EPI == EPI_FF1 || EPI == EPI_SCALE) && G == 256 && (NT == 32 || NT == 16) && tl < (tiles & ~255)) {
;       const int rr = tl >> 8, bb = tl & 255;
;       const int xx = bb & 7, jj = bb >> 3;
;       if (NT == 32) { mt = rr * 8 + (xx >> 2) * 4 + (jj >> 3); nt = (xx & 3) * 8 + (jj & 7); }
;       else { mt = rr * 16 + (xx >> 1) * 4 + (jj >> 3); nt = (xx & 1) * 8 + (jj & 7); }
;     }
.Lgc_unit:
	s_cmp_ge_u32 s5, s38
	s_cbranch_scc1 .Lgm_exit
	s_mov_b32 s47, 0
	s_cmp_ge_u32 s5, s28
	s_cbranch_scc1 .Lgm_split_c
	s_mov_b32 s8, 0
	s_mov_b32 s9, s39
	s_mov_b32 s10, 0
	s_cmp_eq_u32 s27, 0
	s_cbranch_scc1 .Lgm_plain_c
	s_cmp_ge_u32 s5, s29
	s_cbranch_scc1 .Lgm_plain_c
	s_cmp_eq_u32 s27, 4
	s_cbranch_scc0 .Lgm_mapped_c
	s_and_b32 s36, s5, 0xffffff00
	s_and_b32 s37, s5, 7
	s_lshl_b32 s37, s37, 5
	s_or_b32 s36, s36, s37
	s_bfe_u32 s37, s5, 0x50003
	s_or_b32 s36, s36, s37
	s_branch .Lgm_plain2_c
.Lgm_mapped_c:
	s_lshr_b32 s6, s5, 8
	s_and_b32 s7, s5, 0xff
	s_and_b32 s36, s7, 7
	s_lshr_b32 s37, s7, 3
	s_cmp_eq_u32 s27, 3
	s_cbranch_scc1 .Lgm_map8_c
	s_cmp_eq_u32 s27, 1
	s_cbranch_scc0 .Lgm_map16_c
	s_lshl_b32 s6, s6, 3
	s_lshr_b32 s7, s36, 2
	s_lshl_b32 s7, s7, 2
	s_add_u32 s6, s6, s7
	s_lshr_b32 s7, s37, 3
	s_add_u32 s6, s6, s7
	s_and_b32 s7, s36, 3
	s_lshl_b32 s7, s7, 3
	s_and_b32 s37, s37, 7
	s_add_u32 s7, s7, s37
	s_branch .Lgm_dec_done_c

; template <int EPI>
; __device__ __forceinline__ void gemm_phase(const Params& p, const u16* __restrict__ A, int lda, const u16* __restrict__ BT, int ldb,
;                            int K, int N, u16* __restrict__ outb, int ldo, int resid_in, int boff) {
;     ...
;   for (int un = bstart; un < units; un += G) {
;     int tl = un, kbeg = 0, KT = KTALL;
;     bool part_unit = false;
;     if (un >= t_full) { const int v = un - t_full; tl = t_full + v / split; KT = KTALL / split; kbeg = (v % split) * KT; part_unit = true; }
;     int mt = tl / NT, nt = tl % NT;
;     if (EPI == EPI_RES && NT == 8 && G == 256 && !part_unit) {
;       const int rr = tl >> 8, bb = tl & 255;
;       const int xx = bb & 7, jj = bb >> 3;
;       mt = rr * 32 + xx * 4 + (jj >> 3);
;       nt = jj & 7;
;     } else if ((EPI == EPI_FF1 || EPI == EPI_SCALE) && G == 256 && (NT == 32 || NT == 16) && tl < (tiles & ~255)) {
;       const int rr = tl >> 8, bb = tl & 255;
;       const int xx = bb & 7, jj = bb >> 3;
;       if (NT == 32) { mt = rr * 8 + (xx >> 2) * 4 + (jj >> 3); nt = (xx & 3) * 8 + (jj & 7); }
;       else { mt = rr * 16 + (xx >> 1) * 4 + (jj >> 3); nt = (xx & 1) * 8 + (jj & 7); }
;     }
.Lgp_cnt_done:
	s_mov_b32 s11, 0
	s_mov_b32 s18, 0
	s_cmp_ge_u32 s5, s38
	s_cbranch_scc1 .Lgp_su_done_p0
	s_mov_b32 s47, 0
	s_cmp_ge_u32 s5, s28
	s_cbranch_scc1 .Lgm_split_p0
	s_mov_b32 s8, 0
	s_mov_b32 s9, s39
	s_mov_b32 s10, 0
	s_cmp_eq_u32 s27, 0
	s_cbranch_scc1 .Lgm_plain_p0
	s_cmp_ge_u32 s5, s29
	s_cbranch_scc1 .Lgm_plain_p0
	s_cmp_eq_u32 s27, 4
	s_cbranch_scc0 .Lgm_mapped_p0
	s_and_b32 s36, s5, 0xffffff00
	s_and_b32 s37, s5, 7
	s_lshl_b32 s37, s37, 5
	s_or_b32 s36, s36, s37
	s_bfe_u32 s37, s5, 0x50003
	s_or_b32 s36, s36, s37
	s_branch .Lgm_plain2_p0

; template <int EPI>
; __device__ __forceinline__ void gemm_phase(const Params& p, const u16* __restrict__ A, int lda, const u16* __restrict__ BT, int ldb,
;                            int K, int N, u16* __restrict__ outb, int ldo, int resid_in, int boff) {
;     ...
;   for (int un = bstart; un < units; un += G) {
;     int tl = un, kbeg = 0, KT = KTALL;
;     bool part_unit = false;
;     if (un >= t_full) { const int v = un - t_full; tl = t_full + v / split; KT = KTALL / split; kbeg = (v % split) * KT; part_unit = true; }
;     int mt = tl / NT, nt = tl % NT;
;     if (EPI == EPI_RES && NT == 8 && G == 256 && !part_unit) {
;       const int rr = tl >> 8, bb = tl & 255;
;       const int xx = bb & 7, jj = bb >> 3;
;       mt = rr * 32 + xx * 4 + (jj >> 3);
;       nt = jj & 7;
;     } else if ((EPI == EPI_FF1 || EPI == EPI_SCALE) && G == 256 && (NT == 32 || NT == 16) && tl < (tiles & ~255)) {
;       const int rr = tl >> 8, bb = tl & 255;
;       const int xx = bb & 7, jj = bb >> 3;
;       if (NT == 32) { mt = rr * 8 + (xx >> 2) * 4 + (jj >> 3); nt = (xx & 3) * 8 + (jj & 7); }
;       else { mt = rr * 16 + (xx >> 1) * 4 + (jj >> 3); nt = (xx & 1) * 8 + (jj & 7); }
;     }
;     const int m0 = mt * 256, n0 = nt * 128;
;     const u16* gA = A + (size_t)(m0 + lrow) * lda + lch * 8 + (size_t)kbeg * 64;
;     const u16* gB = BT + (size_t)(n0 + lrow) * ldb + lch * 8 + (size_t)kbeg * 64;
;     uint4 xa0, xa1, xa2, xa3, xb0, xb1;
;     uint4 ya0, ya1, ya2, ya3, yb0, yb1;
.Lgp_is_nop_pa:
	s_add_u32 m0, s31, s32
	s_nop 0
	global_load_lds_dwordx4 v130, s[0:1]
	s_add_u32 m0, m0, 0x400
	s_nop 0
	global_load_lds_dwordx4 v131, s[0:1]
	s_add_u32 m0, m0, 0x400
	s_nop 0
	global_load_lds_dwordx4 v132, s[0:1]
	s_add_u32 m0, m0, 0x400
	s_nop 0
	global_load_lds_dwordx4 v133, s[0:1]
	s_add_u32 m0, m0, 0x400
	s_nop 0
	global_load_lds_dwordx4 v134, s[0:1]
	s_add_u32 m0, m0, 0x400
	s_nop 0
	global_load_lds_dwordx4 v135, s[0:1]
	s_add_u32 m0, m0, 0x400
	s_nop 0
	global_load_lds_dwordx4 v136, s[0:1]
	s_add_u32 m0, m0, 0x400
	s_nop 0
	global_load_lds_dwordx4 v137, s[0:1]
	s_add_u32 m0, s31, s34
	s_nop 0
	global_load_lds_dwordx4 v138, s[2:3]
	s_add_u32 m0, m0, 0x400
	s_nop 0
	global_load_lds_dwordx4 v139, s[2:3]
	s_add_u32 m0, m0, 0x400
	s_nop 0
	global_load_lds_dwordx4 v140, s[2:3]
	s_add_u32 m0, m0, 0x400
	s_nop 0
	global_load_lds_dwordx4 v141, s[2:3]
	s_add_u32 s0, s0, 0x80
	s_addc_u32 s1, s1, 0
	s_add_u32 s2, s2, 0x80
	s_addc_u32 s3, s3, 0
	s_add_u32 s31, s31, 0xc000
	s_cmp_eq_u32 s31, 0x24000
	s_cselect_b32 s31, 0, s31
	s_sub_u32 s18, s18, 1
	s_cmp_lg_u32 s18, 0
	s_cbranch_scc1 .Lgp_is_done_pa
	s_add_u32 s5, s5, s42
	s_mov_b32 s13, s10
	s_mov_b32 s11, 0
	s_mov_b32 s18, 0
	s_cmp_ge_u32 s5, s38
	s_cbranch_scc1 .Lgp_su_done_pau
	s_mov_b32 s47, 0
	s_cmp_ge_u32 s5, s28
	s_cbranch_scc1 .Lgm_split_pau
	s_mov_b32 s8, 0
	s_mov_b32 s9, s39
	s_mov_b32 s10, 0
	s_cmp_eq_u32 s27, 0
	s_cbranch_scc1 .Lgm_plain_pau
	s_cmp_ge_u32 s5, s29
	s_cbranch_scc1 .Lgm_plain_pau
	s_cmp_eq_u32 s27, 4
	s_cbranch_scc0 .Lgm_mapped_pau
	s_and_b32 s36, s5, 0xffffff00
	s_and_b32 s37, s5, 7
	s_lshl_b32 s37, s37, 5
	s_or_b32 s36, s36, s37
	s_bfe_u32 s37, s5, 0x50003
	s_or_b32 s36, s36, s37
	s_branch .Lgm_plain2_pau
